# v30 + MLA attention QK MFMA groups issued same-accumulator back to back
# speedup vs baseline: 1.0175x; 1.0092x over previous
; #define LAS __attribute__((address_space(3)))
; template <int TYPE>
; __device__ __forceinline__ void attn_mfma_unit2(const AttnCtx& A, unsigned char* ws, LAS unsigned char* lds, int tid, const AUnit& u) {
;     ...
;     const int w = __builtin_amdgcn_readfirstlane(tid >> 6), lane = tid & 63, q = lane & 31, h2 = lane >> 5;
;     const bf16_t* Qg; const bf16_t* Kg; const bf16_t* VTg; int ld;
;     if (TYPE == 0) { Qg = A.naq + u.h * 128; Kg = A.nak + u.h * 128; ld = 768; VTg = A.vtin + (size_t)(u.h * 128) * M; }
;     else if (TYPE == 1) { Qg = A.mq + u.h * 192; Kg = A.mk + u.h * 192; ld = 960; VTg = A.vtm + (size_t)(u.h * 128) * M; }
;     else { Qg = A.dq + u.h * 128 + 64 * u.pass; Kg = A.dk + u.h * 128 + 64 * u.pass; ld = 640; VTg = A.vtin + (size_t)(768 + u.h * 128) * M; }
;     ...
;     if (w < 4) __builtin_amdgcn_s_setprio(2); else __builtin_amdgcn_s_setprio(0);
;     ...
;     const int qrow = u.qrow0 + 32 * w + q;
;     bf16x8 qf[NKK];
; #pragma unroll
;     for (int kk = 0; kk < NKK; ++kk) qf[kk] = *(const bf16x8*)(Qg + (size_t)qrow * ld + 16 * kk + 8 * h2);
;     int lo = 0, nlat = u.isctx ? 0 : 64, qr = 0, qc = 0, r0w = 0, c0 = 0;
;     if (TYPE == 0 && !u.isctx) {
;         int a = 4 * u.g - 4; lo = a < 0 ? 0 : (a > 56 ? 56 : a); int hb = 4 * u.g + 3 - 4; hb = hb < 0 ? 0 : (hb > 56 ? 56 : hb); nlat = hb + 8 - lo;
;         qr = 4 * u.g + (w >> 1); qc = 32 * (w & 1) + q; int t = qr - 4; r0w = t < 0 ? 0 : (t > 56 ? 56 : t); t = qc - 8; c0 = t < 0 ? 0 : (t > 48 ? 48 : t);
;         LAS float* rp = (LAS float*)(lds + A2_RPB);
;         if (tid < 465) rp[tid] = A.rpb[u.h * 465 + tid] * LOG2E;
;     }
;     const int nt = 4 + nlat;
;     unsigned goff[NIW];
; #pragma unroll
;     for (int m = 0; m < NIW; ++m) {
;         if (m < NIK) { const int p = 64 * (w + 8 * m) + lane, row = p / NKC, slot = p % NKC; const int c = DQK == 128 ? (slot ^ (row & 15)) : (slot ^ ((row >> 1) & 7)); goff[m] = (unsigned)(swap23(row) * ld + 8 * c); }
;         else { const int p = 64 * (w + 8 * (m - NIK)) + lane, ch = p >> 3, slot = p & 7; const int c = slot ^ ((ch >> 1) & 7); goff[m] = (unsigned)(ch * M + 8 * c); }
;     }
;     const unsigned ldsw = (unsigned)w * 1024u;
;     unsigned kbase[NKB], vbase[4];
; #pragma unroll
;     for (int i = 0; i < NKB; ++i) kbase[i] = (unsigned)(q * PITCH + 16 * (DQK == 128 ? ((2 * i + h2) ^ (q & 15)) : ((2 * i + h2) ^ ((q >> 1) & 7))));
; #pragma unroll
.LBB0_2901:
	s_mul_i32 s2, s16, 0xc0
	s_ashr_i32 s3, s2, 31
	s_lshl_b64 s[2:3], s[2:3], 1
	s_add_u32 s14, s26, s2
	s_addc_u32 s15, s27, s3
	s_add_u32 s7, s90, s2
	s_addc_u32 s8, s91, s3
	s_lshl_b32 s2, s16, 7
	s_ashr_i32 s3, s2, 31
	s_mul_i32 s6, s16, 0x220000
	s_mul_hi_i32 s10, s2, 0x4400
	s_add_u32 s9, s92, s6
	s_addc_u32 s10, s93, s10
	s_lshl_b32 s6, s12, 5
	v_and_b32_e32 v16, 31, v2
	s_add_i32 s6, s6, s19
	v_bfe_u32 v17, v2, 5, 1
	v_add_u32_e32 v0, s6, v16
	v_mov_b64_e32 v[4:5], s[14:15]
	s_movk_i32 s13, 0x780
	v_mad_i64_i32 v[4:5], s[14:15], v0, s13, v[4:5]
	v_lshlrev_b32_e32 v0, 4, v17
	v_lshl_add_u64 v[4:5], v[4:5], 0, v[0:1]
	s_and_b32 s13, s11, 0xffffffc0
	v_mov_b32_e32 v0, s11
	s_movk_i32 s11, 0xffc0
	v_bfi_b32 v0, s11, v0, v2
	s_mov_b32 s14, 0x2aaaaaab
	global_load_dwordx4 v[112:115], v[4:5], off
	global_load_dwordx4 v[116:119], v[4:5], off offset:32
	global_load_dwordx4 v[120:123], v[4:5], off offset:64
	global_load_dwordx4 v[124:127], v[4:5], off offset:96
	global_load_dwordx4 v[128:131], v[4:5], off offset:128
	global_load_dwordx4 v[132:135], v[4:5], off offset:160
	global_load_dwordx4 v[136:139], v[4:5], off offset:192
	global_load_dwordx4 v[140:143], v[4:5], off offset:224
	global_load_dwordx4 v[144:147], v[4:5], off offset:256
	global_load_dwordx4 v[148:151], v[4:5], off offset:288
	global_load_dwordx4 v[152:155], v[4:5], off offset:320
	global_load_dwordx4 v[156:159], v[4:5], off offset:352
	v_mul_hi_i32 v4, v0, s14
	v_lshrrev_b32_e32 v5, 31, v4
	v_ashrrev_i32_e32 v4, 2, v4
	v_add_u32_e32 v4, v4, v5
	v_mul_lo_u32 v5, v4, 24
	v_sub_u32_e32 v5, v0, v5
	v_lshrrev_b32_e32 v6, 1, v4
	v_and_b32_e32 v7, 0x3fffff3, v4
	v_lshlrev_b32_e32 v4, 1, v4
	v_bitop3_b32 v5, v6, v5, 7 bitop3:0x6c
	v_and_b32_e32 v4, 8, v4
	v_and_b32_e32 v6, 4, v6
	v_or3_b32 v4, v7, v4, v6
	s_movk_i32 s11, 0x3c0
	v_mul_lo_u32 v4, v4, s11
	s_waitcnt vmcnt(0)
	v_lshl_add_u32 v160, v5, 3, v4
	v_add_u32_e32 v4, 0x200, v0
	v_mul_hi_i32 v5, v4, s14
	v_lshrrev_b32_e32 v6, 31, v5
	v_ashrrev_i32_e32 v5, 2, v5
	v_add_u32_e32 v5, v5, v6
	v_mul_lo_u32 v6, v5, 24
	v_sub_u32_e32 v4, v4, v6
	v_lshrrev_b32_e32 v6, 1, v5
	v_and_b32_e32 v7, 0x3fffff3, v5
	v_lshlrev_b32_e32 v5, 1, v5
	v_bitop3_b32 v4, v6, v4, 7 bitop3:0x6c
	v_and_b32_e32 v5, 8, v5
	v_and_b32_e32 v6, 4, v6
	v_or3_b32 v5, v7, v5, v6
	v_mul_lo_u32 v5, v5, s11
	v_lshl_add_u32 v162, v4, 3, v5
	v_add_u32_e32 v4, 0x400, v0
	v_mul_hi_i32 v5, v4, s14
	v_lshrrev_b32_e32 v6, 31, v5
	v_ashrrev_i32_e32 v5, 2, v5
	v_add_u32_e32 v5, v5, v6
	v_mul_lo_u32 v6, v5, 24
	v_sub_u32_e32 v4, v4, v6
	v_lshrrev_b32_e32 v6, 1, v5
	v_and_b32_e32 v7, 0x3fffff3, v5
	v_lshlrev_b32_e32 v5, 1, v5
	v_bitop3_b32 v4, v6, v4, 7 bitop3:0x6c
	v_and_b32_e32 v5, 8, v5
	v_and_b32_e32 v6, 4, v6
	v_or3_b32 v5, v7, v5, v6
	v_mul_lo_u32 v5, v5, s11
	v_lshl_add_u32 v164, v4, 3, v5
	v_lshrrev_b32_e32 v4, 3, v0
	v_lshrrev_b32_e32 v0, 4, v0
	v_xor_b32_e32 v0, v0, v2
	s_addk_i32 s13, 0x200
	v_and_b32_e32 v3, 63, v2
	v_mul_lo_u32 v4, v4, s82
	v_lshlrev_b32_e32 v0, 3, v0
	s_and_b64 s[0:1], s[0:1], exec
	v_and_or_b32 v166, v0, 56, v4
	v_or_b32_e32 v0, s13, v3
	s_cselect_b32 s11, 0x44, 4
	s_lshl_b32 s13, s18, 8
	s_mul_i32 s14, s18, 0x78000
	s_add_i32 s0, s13, 0x2000
	s_lshl_b32 s12, s12, 10
	s_ashr_i32 s1, s0, 31
	s_add_i32 s14, s14, 0xf00000
	s_mul_hi_i32 s15, s0, 0x780
	s_add_u32 s14, s7, s14
	v_mov_b32_e32 v161, v1
	s_addc_u32 s15, s8, s15
	s_add_i32 s12, s12, 0
	v_lshlrev_b64 v[4:5], 1, v[160:161]
	v_lshl_add_u64 v[6:7], s[14:15], 0, v[4:5]
	s_mov_b32 m0, s12
	v_mov_b32_e32 v163, v1
	global_load_lds_dwordx4 v[6:7], off
	v_lshlrev_b64 v[6:7], 1, v[162:163]
	v_lshl_add_u64 v[8:9], s[14:15], 0, v[6:7]
	s_add_i32 m0, s12, 0x2000
	v_mov_b32_e32 v165, v1
	global_load_lds_dwordx4 v[8:9], off
	v_lshlrev_b64 v[8:9], 1, v[164:165]
	v_lshrrev_b32_e32 v3, 4, v0
	v_lshl_add_u64 v[10:11], s[14:15], 0, v[8:9]
	s_add_i32 m0, s12, 0x4000
	s_lshl_b64 s[14:15], s[0:1], 1
	v_xor_b32_e32 v3, v3, v2
	v_lshrrev_b32_e32 v0, 3, v0
	s_add_u32 s14, s9, s14
	v_mov_b32_e32 v167, v1
	v_lshlrev_b32_e32 v3, 3, v3
	v_mul_lo_u32 v0, v0, s82
	global_load_lds_dwordx4 v[10:11], off
	s_addc_u32 s15, s10, s15
	v_lshlrev_b64 v[10:11], 1, v[166:167]
	v_and_or_b32 v168, v3, 56, v0
	s_add_i32 m0, s12, 0x6000
	v_lshl_add_u64 v[12:13], s[14:15], 0, v[10:11]
	v_mov_b32_e32 v169, v1
	global_load_lds_dwordx4 v[12:13], off
	v_lshlrev_b64 v[12:13], 1, v[168:169]
	v_lshl_add_u64 v[14:15], s[14:15], 0, v[12:13]
	s_add_i32 s14, s13, 0x2040
	s_add_i32 m0, s12, 0x8000
	s_ashr_i32 s15, s14, 31
	s_mul_i32 s13, s14, 0x780
	global_load_lds_dwordx4 v[14:15], off
	s_mul_hi_i32 s1, s14, 0x780
	s_add_u32 s28, s7, s13
	s_waitcnt lgkmcnt(0)
	s_addc_u32 s29, s8, s1
	s_waitcnt vmcnt(0)
	s_barrier
; #define A2_WAITN(n) asm volatile("s_waitcnt vmcnt(%0)" :: "n"(n) : "memory")
; #define A2_BAR() do { __builtin_amdgcn_s_barrier(); asm volatile("" ::: "memory"); } while (0)
; #define A2_SETKC(SOFF) _Pragma("unroll") for (int _i = 0; _i < NKB; ++_i) kc[_i] = kbase[_i] + (unsigned)(SOFF)
; #define A2_SETVC(SOFF) _Pragma("unroll") for (int _i = 0; _i < 4; ++_i) vc[_i] = vbase[_i] + (unsigned)(SOFF)
; template <int TYPE>
; __device__ __forceinline__ void attn_mfma_unit2(const AttnCtx& A, unsigned char* ws, LAS unsigned char* lds, int tid, const AUnit& u) {
;     ...
;         for (int ti = 0; ti < nt; ++ti) {
;             if (ti + 1 < nt) A2_DMA(ti + 1, snxt);
;             if (actP) { A2_SETVC(sprv); A2_FSM_PV(sA0, sA1, 0); }
;             actP = A2_ACTIVE(ti);
;             if (actP) { A2_SETKC(scur); A2_QK(sA0, sA1, ti, 0); A2_PSM(sA0, sA1); }
;             A2_WAITN(0); A2_BAR();
	s_add_i32 m0, s12, 0xa000
	v_lshl_add_u64 v[4:5], s[28:29], 0, v[4:5]
	global_load_lds_dwordx4 v[4:5], off
	v_lshl_add_u64 v[4:5], s[28:29], 0, v[6:7]
	s_add_i32 m0, s12, 0xc000
	s_lshl_b64 s[14:15], s[14:15], 1
	global_load_lds_dwordx4 v[4:5], off
	s_add_i32 m0, s12, 0xe000
	s_add_u32 s14, s9, s14
	v_lshl_add_u64 v[4:5], s[28:29], 0, v[8:9]
	s_addc_u32 s15, s10, s15
	global_load_lds_dwordx4 v[4:5], off
	s_add_i32 m0, s12, 0x10000
	v_lshl_add_u64 v[4:5], s[14:15], 0, v[10:11]
	global_load_lds_dwordx4 v[4:5], off
	v_lshl_add_u64 v[4:5], s[14:15], 0, v[12:13]
	s_add_i32 m0, s12, 0x12000
	v_lshrrev_b32_e32 v0, 1, v2
	global_load_lds_dwordx4 v[4:5], off
	v_bfe_u32 v2, v2, 1, 3
	v_bitop3_b32 v0, v17, v0, 7 bitop3:0x78
	v_bitop3_b32 v3, v17, v2, 2 bitop3:0x36
	v_bitop3_b32 v4, v17, v2, 4 bitop3:0x36
	v_bitop3_b32 v2, v17, v2, 6 bitop3:0x36
	v_lshl_add_u32 v66, v4, 4, 0
	s_movk_i32 s1, 0x180
	v_lshl_add_u32 v67, v2, 4, 0
	v_lshl_add_u32 v68, v3, 4, 0
	v_lshl_add_u32 v0, v0, 4, 0
	v_mad_u32_u24 v170, v16, s1, v66
	v_mad_u32_u24 v172, v16, s1, v67
	v_mad_u32_u24 v173, v16, s1, v68
	v_mad_u32_u24 v174, v16, s1, v0
	ds_read_b128 v[34:37], v170
	ds_read_b128 v[38:41], v170 offset:12288
	ds_read_b128 v[42:45], v172
	ds_read_b128 v[46:49], v172 offset:12288
	ds_read_b128 v[50:53], v173 offset:12288
	ds_read_b128 v[54:57], v173
	ds_read_b128 v[58:61], v174 offset:12288
	ds_read_b128 v[62:65], v174
	s_mov_b32 s29, 1
	v_lshlrev_b32_e32 v69, 7, v16
	s_mov_b32 s1, 0xa000
	v_readlane_b32 s64, v254, 25
	v_readlane_b32 s65, v254, 26
	v_readlane_b32 s66, v254, 27
	v_readlane_b32 s67, v254, 28
	v_readlane_b32 s68, v254, 29
	v_readlane_b32 s69, v254, 30
	v_readlane_b32 s70, v254, 31
	v_readlane_b32 s71, v254, 32
	v_readlane_b32 s72, v254, 33
	v_readlane_b32 s73, v254, 34
	v_readlane_b32 s74, v254, 35
	v_readlane_b32 s75, v254, 36
	v_readlane_b32 s76, v254, 37
	v_readlane_b32 s77, v254, 38
	v_readlane_b32 s78, v254, 39
	v_readlane_b32 s79, v254, 40
	s_mov_b32 s65, s64
	s_mov_b32 s66, s64
	s_mov_b32 s67, s64
	s_mov_b32 s68, s64
	s_mov_b32 s69, s64
	s_mov_b32 s70, s64
	s_mov_b32 s71, s64
	s_mov_b32 s72, s64
	s_mov_b32 s73, s64
	s_mov_b32 s74, s64
	s_mov_b32 s75, s64
	s_mov_b32 s76, s64
	s_mov_b32 s77, s64
	s_mov_b32 s78, s64
	s_mov_b32 s79, s64
	v_mov_b64_e32 v[2:3], s[64:65]
	s_mov_b32 s36, s64
	v_mov_b64_e32 v[4:5], s[66:67]
	v_mov_b64_e32 v[6:7], s[68:69]
	v_mov_b64_e32 v[8:9], s[70:71]
	v_mov_b64_e32 v[10:11], s[72:73]
	v_mov_b64_e32 v[12:13], s[74:75]
	v_mov_b64_e32 v[14:15], s[76:77]
	v_mov_b64_e32 v[16:17], s[78:79]
	v_writelane_b32 v254, s36, 25
	s_waitcnt lgkmcnt(0)
	v_mfma_f32_32x32x16_bf16 v[18:33], v[62:65], v[112:115], v[2:17]
	v_writelane_b32 v254, s37, 26
	v_writelane_b32 v254, s38, 27
	v_writelane_b32 v254, s39, 28
	v_writelane_b32 v254, s40, 29
	v_writelane_b32 v254, s41, 30
	v_writelane_b32 v254, s42, 31
	v_writelane_b32 v254, s43, 32
	v_mfma_f32_32x32x16_bf16 v[2:17], v[58:61], v[112:115], v[2:17]
	v_writelane_b32 v254, s44, 33
	v_writelane_b32 v254, s45, 34
	v_writelane_b32 v254, s46, 35
	v_writelane_b32 v254, s47, 36
	v_writelane_b32 v254, s48, 37
	v_writelane_b32 v254, s49, 38
	v_writelane_b32 v254, s50, 39
	v_mfma_f32_32x32x16_bf16 v[18:33], v[54:57], v[116:119], v[18:33]
	v_writelane_b32 v254, s51, 40
	v_mfma_f32_32x32x16_bf16 v[2:17], v[50:53], v[116:119], v[2:17]
	ds_read_b128 v[50:53], v173 offset:12416
	ds_read_b128 v[54:57], v173 offset:128
	ds_read_b128 v[58:61], v174 offset:12416
	ds_read_b128 v[62:65], v174 offset:128
	v_mfma_f32_32x32x16_bf16 v[18:33], v[34:37], v[120:123], v[18:33]
	v_mfma_f32_32x32x16_bf16 v[18:33], v[42:45], v[124:127], v[18:33]
	v_mfma_f32_32x32x16_bf16 v[2:17], v[38:41], v[120:123], v[2:17]
	v_mfma_f32_32x32x16_bf16 v[2:17], v[46:49], v[124:127], v[2:17]
	ds_read_b128 v[34:37], v170 offset:128
	ds_read_b128 v[38:41], v170 offset:12416
	ds_read_b128 v[42:45], v172 offset:128
	ds_read_b128 v[46:49], v172 offset:12416
	s_waitcnt lgkmcnt(0)
	v_mfma_f32_32x32x16_bf16 v[18:33], v[62:65], v[128:131], v[18:33]
	v_mfma_f32_32x32x16_bf16 v[18:33], v[54:57], v[132:135], v[18:33]
	v_mfma_f32_32x32x16_bf16 v[2:17], v[58:61], v[128:131], v[2:17]
	v_mfma_f32_32x32x16_bf16 v[2:17], v[50:53], v[132:135], v[2:17]
	ds_read_b128 v[50:53], v173 offset:12544
	ds_read_b128 v[54:57], v173 offset:256
	ds_read_b128 v[58:61], v174 offset:12544
	ds_read_b128 v[62:65], v174 offset:256
	v_mfma_f32_32x32x16_bf16 v[18:33], v[34:37], v[136:139], v[18:33]
	v_mfma_f32_32x32x16_bf16 v[18:33], v[42:45], v[140:143], v[18:33]
	v_mfma_f32_32x32x16_bf16 v[2:17], v[38:41], v[136:139], v[2:17]
	v_mfma_f32_32x32x16_bf16 v[2:17], v[46:49], v[140:143], v[2:17]
	ds_read_b128 v[34:37], v170 offset:256
	ds_read_b128 v[38:41], v170 offset:12544
	ds_read_b128 v[42:45], v172 offset:256
	ds_read_b128 v[46:49], v172 offset:12544
	s_waitcnt lgkmcnt(0)
	v_mfma_f32_32x32x16_bf16 v[18:33], v[62:65], v[144:147], v[18:33]
	v_mfma_f32_32x32x16_bf16 v[18:33], v[54:57], v[148:151], v[18:33]
	v_mfma_f32_32x32x16_bf16 v[2:17], v[58:61], v[144:147], v[2:17]
	v_mfma_f32_32x32x16_bf16 v[2:17], v[50:53], v[148:151], v[2:17]
	v_mfma_f32_32x32x16_bf16 v[18:33], v[34:37], v[152:155], v[18:33]
	v_mfma_f32_32x32x16_bf16 v[18:33], v[42:45], v[156:159], v[18:33]
	v_mfma_f32_32x32x16_bf16 v[2:17], v[38:41], v[152:155], v[2:17]
	s_nop 10
	v_max_f32_e32 v34, v19, v19
	v_max_f32_e32 v35, v18, v18
	v_max_f32_e32 v34, v35, v34
	v_max3_f32 v34, v34, v20, v21
	v_max3_f32 v34, v34, v22, v23
	v_max3_f32 v34, v34, v24, v25
	v_max3_f32 v34, v34, v26, v27
	v_mfma_f32_32x32x16_bf16 v[2:17], v[46:49], v[156:159], v[2:17]
	v_max3_f32 v34, v34, v28, v29
	v_max3_f32 v34, v34, v30, v31
	v_max3_f32 v34, v34, v32, v33
	s_waitcnt vmcnt(0)
	s_barrier
; #define A2_WAITN(n) asm volatile("s_waitcnt vmcnt(%0)" :: "n"(n) : "memory")
; #define A2_BAR() do { __builtin_amdgcn_s_barrier(); asm volatile("" ::: "memory"); } while (0)
; #define A2_SETKC(SOFF) _Pragma("unroll") for (int _i = 0; _i < NKB; ++_i) kc[_i] = kbase[_i] + (unsigned)(SOFF)
; #define A2_SETVC(SOFF) _Pragma("unroll") for (int _i = 0; _i < 4; ++_i) vc[_i] = vbase[_i] + (unsigned)(SOFF)
; template <int TYPE>
; __device__ __forceinline__ void attn_mfma_unit2(const AttnCtx& A, unsigned char* ws, LAS unsigned char* lds, int tid, const AUnit& u) {
;     ...
;         bool actP = false;
;         for (int ti = 0; ti < nt; ++ti) {
;             if (ti + 1 < nt) A2_DMA(ti + 1, snxt);
;             if (actP) { A2_SETVC(sprv); A2_FSM_PV(sA0, sA1, 0); }
;             actP = A2_ACTIVE(ti);
;             if (actP) { A2_SETKC(scur); A2_QK(sA0, sA1, ti, 0); A2_PSM(sA0, sA1); }
;             A2_WAITN(0); A2_BAR();
;             sprv = scur; scur = snxt; snxt = snxt == 2 * STG ? 0 : snxt + STG;
;         }
	v_add_u32_e32 v183, v0, v69
	s_nop 6
	v_max3_f32 v34, v34, v2, v3
	v_max3_f32 v34, v34, v4, v5
	v_max3_f32 v34, v34, v6, v7
	v_max3_f32 v34, v34, v8, v9
	v_max3_f32 v34, v34, v10, v11
	v_max3_f32 v34, v34, v12, v13
	v_max3_f32 v34, v34, v14, v15
	v_max3_f32 v34, v34, v16, v17
	v_mov_b32_e32 v35, v34
	s_nop 1
	v_permlane32_swap_b32_e32 v34, v35
	v_max_f32_e32 v35, v35, v35
	v_max_f32_e32 v34, v34, v34
	v_max_f32_e32 v34, v34, v35
	v_sub_f32_e32 v93, v15, v34
	v_sub_f32_e32 v92, v14, v34
	v_mov_b32_e32 v14, v1
	v_mov_b32_e32 v15, v1
	v_add_f32_e32 v181, 0, v34
	v_sub_f32_e32 v111, v33, v34
	v_sub_f32_e32 v110, v32, v34
	v_sub_f32_e32 v109, v31, v34
	v_sub_f32_e32 v108, v30, v34
	v_sub_f32_e32 v107, v29, v34
	v_sub_f32_e32 v106, v28, v34
	v_sub_f32_e32 v105, v27, v34
	v_sub_f32_e32 v104, v26, v34
	v_sub_f32_e32 v103, v25, v34
	v_sub_f32_e32 v102, v24, v34
	v_sub_f32_e32 v101, v23, v34
	v_sub_f32_e32 v100, v22, v34
	v_sub_f32_e32 v99, v21, v34
	v_sub_f32_e32 v98, v20, v34
	v_sub_f32_e32 v97, v19, v34
	v_sub_f32_e32 v96, v18, v34
	v_sub_f32_e32 v95, v17, v34
	v_sub_f32_e32 v94, v16, v34
	v_sub_f32_e32 v91, v13, v34
	v_sub_f32_e32 v90, v12, v34
	v_sub_f32_e32 v89, v11, v34
	v_sub_f32_e32 v88, v10, v34
	v_sub_f32_e32 v87, v9, v34
	v_sub_f32_e32 v86, v8, v34
	v_sub_f32_e32 v85, v7, v34
	v_sub_f32_e32 v84, v6, v34
	v_sub_f32_e32 v83, v5, v34
	v_sub_f32_e32 v82, v4, v34
	v_sub_f32_e32 v81, v3, v34
	v_sub_f32_e32 v80, v2, v34
	v_add_u32_e32 v182, v68, v69
	v_add_u32_e32 v180, v66, v69
	v_add_u32_e32 v175, v67, v69
	s_lshl_b32 s13, s18, 12
	v_mov_b32_e32 v0, v1
	v_mov_b32_e32 v2, v1
	v_mov_b32_e32 v3, v1
	v_mov_b32_e32 v4, v1
	v_mov_b32_e32 v5, v1
	v_mov_b32_e32 v6, v1
	v_mov_b32_e32 v7, v1
	v_mov_b32_e32 v8, v1
	v_mov_b32_e32 v9, v1
	v_mov_b32_e32 v10, v1
	v_mov_b32_e32 v11, v1
	v_mov_b32_e32 v12, v1
	v_mov_b32_e32 v13, v1
	v_mov_b64_e32 v[30:31], v[14:15]
	v_mov_b64_e32 v[46:47], v[14:15]
	v_mov_b64_e32 v[62:63], v[14:15]
	v_mov_b64_e32 v[78:79], v[14:15]
	s_mov_b32 s28, 0
	s_addk_i32 s13, 0xff40
	s_mov_b32 s36, 0x14000
	v_mov_b32_e32 v171, 0
	v_mov_b64_e32 v[28:29], v[12:13]
	v_mov_b64_e32 v[26:27], v[10:11]
	v_mov_b64_e32 v[24:25], v[8:9]
	v_mov_b64_e32 v[22:23], v[6:7]
	v_mov_b64_e32 v[20:21], v[4:5]
	v_mov_b64_e32 v[18:19], v[2:3]
	v_mov_b64_e32 v[16:17], v[0:1]
	v_mov_b64_e32 v[44:45], v[12:13]
	v_mov_b64_e32 v[42:43], v[10:11]
	v_mov_b64_e32 v[40:41], v[8:9]
	v_mov_b64_e32 v[38:39], v[6:7]
	v_mov_b64_e32 v[36:37], v[4:5]
	v_mov_b64_e32 v[34:35], v[2:3]
	v_mov_b64_e32 v[32:33], v[0:1]
	v_mov_b64_e32 v[60:61], v[12:13]
	v_mov_b64_e32 v[58:59], v[10:11]
	v_mov_b64_e32 v[56:57], v[8:9]
	v_mov_b64_e32 v[54:55], v[6:7]
	v_mov_b64_e32 v[52:53], v[4:5]
	v_mov_b64_e32 v[50:51], v[2:3]
	v_mov_b64_e32 v[48:49], v[0:1]
	v_mov_b64_e32 v[76:77], v[12:13]
	v_mov_b64_e32 v[74:75], v[10:11]
	v_mov_b64_e32 v[72:73], v[8:9]
	v_mov_b64_e32 v[70:71], v[6:7]
	v_mov_b64_e32 v[68:69], v[4:5]
	v_mov_b64_e32 v[66:67], v[2:3]
	v_mov_b64_e32 v[64:65], v[0:1]
	s_add_i32 s15, s29, 1
	s_mov_b32 s14, s36
	s_cmp_ge_u32 s15, s11
	s_cbranch_scc1 .LBB0_2904
	s_branch .LBB0_2903

.LBB0_2904:
	v_add_u32_e32 v0, s28, v183
	ds_read_b128 v[2:5], v0 offset:24576
	ds_read_b128 v[6:9], v0 offset:28672
	ds_read_b128 v[10:13], v0 offset:32768
	ds_read_b128 v[184:187], v0 offset:36864
	v_exp_f32_e32 v14, v96
	v_exp_f32_e32 v190, v97
	v_exp_f32_e32 v98, v98
	v_exp_f32_e32 v192, v99
	v_exp_f32_e32 v15, v100
	v_exp_f32_e32 v191, v101
	v_exp_f32_e32 v99, v102
	v_exp_f32_e32 v193, v103
	v_add_u32_e32 v0, s28, v182
	v_pk_add_f32 v[96:97], v[14:15], v[190:191]
	v_pk_add_f32 v[100:101], v[98:99], v[192:193]
	s_nop 0
	v_pk_add_f32 v[96:97], v[96:97], v[100:101]
	v_cvt_pk_bf16_f32 v99, v99, v193
	v_pk_add_f32 v[202:203], v[96:97], v[96:97] op_sel_hi:[0,1]
	v_cvt_pk_bf16_f32 v96, v14, v190
	v_cvt_pk_bf16_f32 v97, v98, v192
	v_cvt_pk_bf16_f32 v98, v15, v191
	ds_read_b128 v[100:103], v0 offset:24576
	ds_read_b128 v[190:193], v0 offset:28672
	ds_read_b128 v[194:197], v0 offset:32768
	ds_read_b128 v[198:201], v0 offset:36864
	s_waitcnt lgkmcnt(0)
	v_mfma_f32_32x32x16_bf16 v[64:79], v[2:5], v[96:99], v[64:79]
	v_mfma_f32_32x32x16_bf16 v[48:63], v[6:9], v[96:99], v[48:63]
	v_mfma_f32_32x32x16_bf16 v[32:47], v[10:13], v[96:99], v[32:47]
	v_mfma_f32_32x32x16_bf16 v[16:31], v[184:187], v[96:99], v[16:31]
	v_exp_f32_e32 v2, v104
	v_exp_f32_e32 v4, v105
	v_exp_f32_e32 v3, v106
	v_exp_f32_e32 v5, v107
	v_exp_f32_e32 v6, v108
	v_exp_f32_e32 v8, v109
	v_exp_f32_e32 v7, v110
	v_exp_f32_e32 v9, v111
	v_pk_add_f32 v[10:11], v[2:3], v[4:5]
	v_add_u32_e32 v0, s28, v180
	v_pk_add_f32 v[14:15], v[10:11], v[10:11] op_sel_hi:[0,1]
	v_pk_add_f32 v[10:11], v[6:7], v[8:9]
	v_cvt_pk_bf16_f32 v2, v2, v4
	v_pk_add_f32 v[184:185], v[10:11], v[10:11] op_sel_hi:[0,1]
	v_cvt_pk_bf16_f32 v3, v3, v5
	v_cvt_pk_bf16_f32 v4, v6, v8
	v_cvt_pk_bf16_f32 v5, v7, v9
	ds_read_b128 v[6:9], v0 offset:24576
	ds_read_b128 v[10:13], v0 offset:28672
	ds_read_b128 v[96:99], v0 offset:32768
	ds_read_b128 v[104:107], v0 offset:36864
	v_mfma_f32_32x32x16_bf16 v[64:79], v[100:103], v[2:5], v[64:79]
	v_mfma_f32_32x32x16_bf16 v[48:63], v[190:193], v[2:5], v[48:63]
	v_mfma_f32_32x32x16_bf16 v[32:47], v[194:197], v[2:5], v[32:47]
	v_mfma_f32_32x32x16_bf16 v[16:31], v[198:201], v[2:5], v[16:31]
	v_exp_f32_e32 v0, v80
	v_exp_f32_e32 v2, v81
	v_exp_f32_e32 v3, v82
	v_exp_f32_e32 v4, v83
	v_exp_f32_e32 v5, v84
	v_exp_f32_e32 v14, v85
	v_exp_f32_e32 v80, v86
	v_exp_f32_e32 v81, v87
	v_add_f32_e32 v187, v0, v2
	v_cvt_pk_bf16_f32 v2, v0, v2
	v_add_u32_e32 v0, s28, v175
	v_add_f32_e32 v191, v3, v4
	v_add_f32_e32 v193, v5, v14
	v_add_f32_e32 v195, v80, v81
	v_cvt_pk_bf16_f32 v3, v3, v4
	v_cvt_pk_bf16_f32 v4, v5, v14
	v_cvt_pk_bf16_f32 v5, v80, v81
	ds_read_b128 v[80:83], v0 offset:24576
	ds_read_b128 v[84:87], v0 offset:28672
	ds_read_b128 v[100:103], v0 offset:32768
	ds_read_b128 v[108:111], v0 offset:36864
	s_waitcnt lgkmcnt(0)
	v_mfma_f32_32x32x16_bf16 v[64:79], v[6:9], v[2:5], v[64:79]
	v_mfma_f32_32x32x16_bf16 v[48:63], v[10:13], v[2:5], v[48:63]
	v_mfma_f32_32x32x16_bf16 v[32:47], v[96:99], v[2:5], v[32:47]
	v_mfma_f32_32x32x16_bf16 v[16:31], v[104:107], v[2:5], v[16:31]
	v_exp_f32_e32 v186, v88
	v_exp_f32_e32 v190, v89
	v_exp_f32_e32 v192, v90
	v_exp_f32_e32 v194, v91
	v_exp_f32_e32 v14, v92
	v_exp_f32_e32 v184, v93
	v_exp_f32_e32 v202, v94
	v_exp_f32_e32 v0, v95
	v_cvt_pk_bf16_f32 v2, v186, v190
	v_cvt_pk_bf16_f32 v3, v192, v194
	v_cvt_pk_bf16_f32 v4, v14, v184
	v_cvt_pk_bf16_f32 v5, v202, v0
	s_nop 1
	v_mfma_f32_32x32x16_bf16 v[64:79], v[80:83], v[2:5], v[64:79]
	v_add_f32_e64 v6, v186, v190
	v_add_f32_e64 v7, v187, v191
	v_add_f32_e64 v8, v192, v194
	v_add_f32_e64 v9, v193, v195
	v_add_f32_e64 v10, v202, v0
	v_add_f32_e64 v11, v203, v1
	v_pk_add_f32 v[6:7], v[6:7], v[8:9]
	v_pk_add_f32 v[8:9], v[14:15], v[184:185]
	s_nop 0
	v_pk_add_f32 v[8:9], v[8:9], v[10:11]
	v_mfma_f32_32x32x16_bf16 v[48:63], v[84:87], v[2:5], v[48:63]
	v_add_f32_e64 v6, v6, v8
	v_add_f32_e64 v7, v7, v9
	v_pk_add_f32 v[6:7], v[6:7], v[6:7] op_sel:[0,1] op_sel_hi:[1,0]
	v_mfma_f32_32x32x16_bf16 v[32:47], v[100:103], v[2:5], v[32:47]
	v_mfma_f32_32x32x16_bf16 v[16:31], v[108:111], v[2:5], v[16:31]
	v_mov_b32_e32 v0, v6
	s_nop 1
	v_permlane32_swap_b32_e32 v6, v0
	v_add_f32_e32 v0, v6, v0
	v_add_f32_e32 v171, v171, v0
	v_add_u32_e32 v0, s1, v174
	v_add_u32_e32 v14, s1, v173
	v_add_u32_e32 v15, s1, v170
	ds_read_b128 v[2:5], v0
	ds_read_b128 v[6:9], v0 offset:12288
	ds_read_b128 v[10:13], v14
	ds_read_b128 v[184:187], v14 offset:12288
	v_add_u32_e32 v206, s1, v172
	ds_read_b128 v[190:193], v15
	ds_read_b128 v[194:197], v15 offset:12288
	ds_read_b128 v[198:201], v206
	ds_read_b128 v[202:205], v206 offset:12288
	v_xor_b32_e32 v80, 0x80000000, v181
	v_mov_b32_e32 v81, v80
	v_mov_b32_e32 v82, v80
	v_mov_b32_e32 v83, v80
	v_mov_b32_e32 v84, v80
	v_mov_b32_e32 v85, v80
	v_mov_b32_e32 v86, v80
	v_mov_b32_e32 v87, v80
	v_mov_b32_e32 v88, v80
	v_mov_b32_e32 v89, v80
	v_mov_b32_e32 v90, v80
	v_mov_b32_e32 v91, v80
	v_mov_b32_e32 v92, v80
	v_mov_b32_e32 v93, v80
	v_mov_b32_e32 v94, v80
	v_mov_b32_e32 v95, v80
	s_waitcnt lgkmcnt(0)
	s_nop 0
	v_mfma_f32_32x32x16_bf16 v[96:111], v[2:5], v[112:115], v[80:95]
	v_mfma_f32_32x32x16_bf16 v[80:95], v[6:9], v[112:115], v[80:95]
	v_mfma_f32_32x32x16_bf16 v[96:111], v[10:13], v[116:119], v[96:111]
	v_mfma_f32_32x32x16_bf16 v[80:95], v[184:187], v[116:119], v[80:95]
	ds_read_b128 v[2:5], v14 offset:12416
	ds_read_b128 v[6:9], v14 offset:128
	ds_read_b128 v[10:13], v0 offset:12416
	ds_read_b128 v[184:187], v0 offset:128
	v_mfma_f32_32x32x16_bf16 v[96:111], v[190:193], v[120:123], v[96:111]
	v_mfma_f32_32x32x16_bf16 v[96:111], v[198:201], v[124:127], v[96:111]
	v_mfma_f32_32x32x16_bf16 v[80:95], v[194:197], v[120:123], v[80:95]
	v_mfma_f32_32x32x16_bf16 v[80:95], v[202:205], v[124:127], v[80:95]
	ds_read_b128 v[190:193], v15 offset:128
	ds_read_b128 v[194:197], v15 offset:12416
	ds_read_b128 v[198:201], v206 offset:128
	ds_read_b128 v[202:205], v206 offset:12416
	s_waitcnt lgkmcnt(0)
	v_mfma_f32_32x32x16_bf16 v[96:111], v[184:187], v[128:131], v[96:111]
	v_mfma_f32_32x32x16_bf16 v[96:111], v[6:9], v[132:135], v[96:111]
	v_mfma_f32_32x32x16_bf16 v[80:95], v[10:13], v[128:131], v[80:95]
	v_mfma_f32_32x32x16_bf16 v[80:95], v[2:5], v[132:135], v[80:95]
	ds_read_b128 v[2:5], v14 offset:12544
	ds_read_b128 v[6:9], v14 offset:256
	ds_read_b128 v[10:13], v0 offset:12544
	ds_read_b128 v[184:187], v0 offset:256
	v_mfma_f32_32x32x16_bf16 v[96:111], v[190:193], v[136:139], v[96:111]
	v_mfma_f32_32x32x16_bf16 v[96:111], v[198:201], v[140:143], v[96:111]
	v_mfma_f32_32x32x16_bf16 v[80:95], v[194:197], v[136:139], v[80:95]
	v_mfma_f32_32x32x16_bf16 v[80:95], v[202:205], v[140:143], v[80:95]
	ds_read_b128 v[190:193], v15 offset:256
	ds_read_b128 v[194:197], v15 offset:12544
	ds_read_b128 v[198:201], v206 offset:256
	ds_read_b128 v[202:205], v206 offset:12544
	s_waitcnt lgkmcnt(0)
	v_mfma_f32_32x32x16_bf16 v[96:111], v[184:187], v[144:147], v[96:111]
	v_mfma_f32_32x32x16_bf16 v[96:111], v[6:9], v[148:151], v[96:111]
	v_mfma_f32_32x32x16_bf16 v[80:95], v[10:13], v[144:147], v[80:95]
	v_mfma_f32_32x32x16_bf16 v[80:95], v[2:5], v[148:151], v[80:95]
	v_mfma_f32_32x32x16_bf16 v[96:111], v[190:193], v[152:155], v[96:111]
	v_mfma_f32_32x32x16_bf16 v[96:111], v[198:201], v[156:159], v[96:111]
	v_mfma_f32_32x32x16_bf16 v[80:95], v[194:197], v[152:155], v[80:95]
	s_nop 10
	v_max_f32_e32 v0, v97, v97
	v_max_f32_e32 v2, v96, v96
	v_max_f32_e32 v0, v2, v0
	v_max3_f32 v0, v0, v98, v99
	v_max3_f32 v0, v0, v100, v101
	v_max3_f32 v0, v0, v102, v103
	v_max3_f32 v0, v0, v104, v105
	v_mfma_f32_32x32x16_bf16 v[80:95], v[202:205], v[156:159], v[80:95]
	v_max3_f32 v0, v0, v106, v107
	v_max3_f32 v0, v0, v108, v109
	v_max3_f32 v0, v0, v110, v111
	s_mov_b32 s28, 0x41000000
	s_nop 7
	v_max3_f32 v0, v0, v80, v81
	v_max3_f32 v0, v0, v82, v83
	v_max3_f32 v0, v0, v84, v85
	v_max3_f32 v0, v0, v86, v87
	v_max3_f32 v0, v0, v88, v89
	v_max3_f32 v0, v0, v90, v91
	v_max3_f32 v0, v0, v92, v93
	v_max3_f32 v0, v0, v94, v95
	v_mov_b32_e32 v2, v0
	s_nop 1
	v_permlane32_swap_b32_e32 v0, v2
	v_max_f32_e32 v2, v2, v2
	v_max_f32_e32 v0, v0, v0
	v_max_f32_e32 v0, v0, v2
	v_cmp_ge_f32_e32 vcc, s28, v0
	s_cmp_eq_u64 vcc, exec
	s_cbranch_scc1 .LBB0_2906
	v_max_f32_e32 v0, v0, v0
	v_max_f32_e32 v2, 0, v0
	v_exp_f32_e64 v0, -v2
	v_add_f32_e32 v181, v181, v2
	v_sub_f32_e32 v111, v111, v2
	v_sub_f32_e32 v110, v110, v2
	v_pk_mul_f32 v[78:79], v[78:79], v[0:1] op_sel_hi:[1,0]
	v_pk_mul_f32 v[76:77], v[76:77], v[0:1] op_sel_hi:[1,0]
	v_pk_mul_f32 v[74:75], v[74:75], v[0:1] op_sel_hi:[1,0]
	v_pk_mul_f32 v[72:73], v[72:73], v[0:1] op_sel_hi:[1,0]
	v_pk_mul_f32 v[70:71], v[70:71], v[0:1] op_sel_hi:[1,0]
	v_pk_mul_f32 v[68:69], v[68:69], v[0:1] op_sel_hi:[1,0]
	v_pk_mul_f32 v[66:67], v[66:67], v[0:1] op_sel_hi:[1,0]
	v_pk_mul_f32 v[64:65], v[64:65], v[0:1] op_sel_hi:[1,0]
	v_pk_mul_f32 v[62:63], v[62:63], v[0:1] op_sel_hi:[1,0]
	v_pk_mul_f32 v[60:61], v[60:61], v[0:1] op_sel_hi:[1,0]
	v_pk_mul_f32 v[58:59], v[58:59], v[0:1] op_sel_hi:[1,0]
	v_pk_mul_f32 v[56:57], v[56:57], v[0:1] op_sel_hi:[1,0]
	v_pk_mul_f32 v[54:55], v[54:55], v[0:1] op_sel_hi:[1,0]
	v_pk_mul_f32 v[52:53], v[52:53], v[0:1] op_sel_hi:[1,0]
	v_pk_mul_f32 v[50:51], v[50:51], v[0:1] op_sel_hi:[1,0]
	v_pk_mul_f32 v[48:49], v[48:49], v[0:1] op_sel_hi:[1,0]
	v_pk_mul_f32 v[46:47], v[46:47], v[0:1] op_sel_hi:[1,0]
	v_pk_mul_f32 v[44:45], v[44:45], v[0:1] op_sel_hi:[1,0]
	v_pk_mul_f32 v[42:43], v[42:43], v[0:1] op_sel_hi:[1,0]
	v_pk_mul_f32 v[40:41], v[40:41], v[0:1] op_sel_hi:[1,0]
	v_pk_mul_f32 v[38:39], v[38:39], v[0:1] op_sel_hi:[1,0]
	v_pk_mul_f32 v[36:37], v[36:37], v[0:1] op_sel_hi:[1,0]
	v_pk_mul_f32 v[34:35], v[34:35], v[0:1] op_sel_hi:[1,0]
	v_pk_mul_f32 v[32:33], v[32:33], v[0:1] op_sel_hi:[1,0]
	v_pk_mul_f32 v[30:31], v[30:31], v[0:1] op_sel_hi:[1,0]
	v_pk_mul_f32 v[28:29], v[28:29], v[0:1] op_sel_hi:[1,0]
	v_pk_mul_f32 v[26:27], v[26:27], v[0:1] op_sel_hi:[1,0]
	v_pk_mul_f32 v[24:25], v[24:25], v[0:1] op_sel_hi:[1,0]
	v_pk_mul_f32 v[22:23], v[22:23], v[0:1] op_sel_hi:[1,0]
	v_pk_mul_f32 v[20:21], v[20:21], v[0:1] op_sel_hi:[1,0]
	v_pk_mul_f32 v[18:19], v[18:19], v[0:1] op_sel_hi:[1,0]
	v_pk_mul_f32 v[16:17], v[16:17], v[0:1] op_sel_hi:[1,0]
	v_sub_f32_e32 v109, v109, v2
	v_sub_f32_e32 v108, v108, v2
	v_sub_f32_e32 v107, v107, v2
	v_sub_f32_e32 v106, v106, v2
	v_sub_f32_e32 v105, v105, v2
	v_sub_f32_e32 v104, v104, v2
	v_sub_f32_e32 v103, v103, v2
	v_sub_f32_e32 v102, v102, v2
	v_sub_f32_e32 v101, v101, v2
	v_sub_f32_e32 v100, v100, v2
	v_sub_f32_e32 v99, v99, v2
	v_sub_f32_e32 v98, v98, v2
	v_sub_f32_e32 v97, v97, v2
	v_sub_f32_e32 v96, v96, v2
	v_sub_f32_e32 v95, v95, v2
	v_sub_f32_e32 v94, v94, v2
	v_sub_f32_e32 v93, v93, v2
	v_sub_f32_e32 v92, v92, v2
	v_sub_f32_e32 v91, v91, v2
	v_sub_f32_e32 v90, v90, v2
	v_sub_f32_e32 v89, v89, v2
	v_sub_f32_e32 v88, v88, v2
	v_sub_f32_e32 v87, v87, v2
	v_sub_f32_e32 v86, v86, v2
	v_sub_f32_e32 v85, v85, v2
	v_sub_f32_e32 v84, v84, v2
	v_sub_f32_e32 v83, v83, v2
	v_sub_f32_e32 v82, v82, v2
	v_sub_f32_e32 v81, v81, v2
	v_sub_f32_e32 v80, v80, v2
	v_mul_f32_e32 v171, v171, v0
